# up-epilogue: conv weights/bias preloaded once per tile into registers, hh loop unrolled; plus attnD hand-scheduled loop and GEMM DMA issue moved into L phase
# speedup vs baseline: 1.0225x; 1.0225x over previous
.LBB0_98:
	v_or_b32_e32 v128, s19, v212
	v_add_u32_e32 v129, v128, v203
	ds_read_b128 v[156:159], v129 offset:0
	ds_read_b128 v[152:155], v129 offset:0x800
	v_add_u32_e32 v129, s19, v211
	ds_read_b128 v[172:175], v129 offset:0
	ds_read_b128 v[168:171], v129 offset:0x800
	ds_read_b128 v[164:167], v129 offset:0x1000
	ds_read_b128 v[160:163], v129 offset:0x1800
	v_add_u32_e32 v136, v128, v204
	ds_read_b128 v[132:135], v136 offset:0
	ds_read_b128 v[128:131], v136 offset:0x800
	v_add_u32_e32 v176, s19, v214
	ds_read_b128 v[148:151], v176 offset:0
	ds_read_b128 v[144:147], v176 offset:0x800
	ds_read_b128 v[140:143], v176 offset:0x1000
	ds_read_b128 v[136:139], v176 offset:0x1800
	s_cmpk_gt_u32 s18, 0x54
	s_cbranch_scc1 .Lgkd_nodma
	s_cmpk_gt_i32 s19, 0x7fff
	s_cselect_b32 s8, s21, 0x18000
	s_add_i32 s8, s8, s19
	s_add_i32 s8, s17, s8
	v_lshl_add_u64 v[234:235], v[186:187], 0, s[6:7]
	s_mov_b32 m0, s8
	s_nop 0
	global_load_lds_dwordx4 v[234:235], off
	v_lshl_add_u64 v[234:235], v[184:185], 0, s[6:7]
	s_add_i32 m0, s8, 0x400
	s_nop 0
	global_load_lds_dwordx4 v[234:235], off
	s_add_i32 m0, s8, 0x4000
	v_lshl_add_u64 v[234:235], v[182:183], 0, s[6:7]
	global_load_lds_dwordx4 v[234:235], off
	v_lshl_add_u64 v[234:235], v[180:181], 0, s[6:7]
	s_add_i32 m0, s8, 0x4400
	s_nop 0
	global_load_lds_dwordx4 v[234:235], off
	s_waitcnt vmcnt(8) lgkmcnt(0)
	s_barrier
.LBB0_102:
	v_mfma_f32_32x32x16_bf16 v[112:127], v[172:175], v[156:159], v[112:127]
	v_mfma_f32_32x32x16_bf16 v[96:111], v[172:175], v[152:155], v[96:111]
	v_mfma_f32_32x32x16_bf16 v[80:95], v[168:171], v[156:159], v[80:95]
	v_mfma_f32_32x32x16_bf16 v[64:79], v[168:171], v[152:155], v[64:79]
	v_mfma_f32_32x32x16_bf16 v[48:63], v[164:167], v[156:159], v[48:63]
	v_mfma_f32_32x32x16_bf16 v[32:47], v[164:167], v[152:155], v[32:47]
	v_mfma_f32_32x32x16_bf16 v[16:31], v[160:163], v[156:159], v[16:31]
	v_mfma_f32_32x32x16_bf16 v[0:15], v[160:163], v[152:155], v[0:15]
	v_mfma_f32_32x32x16_bf16 v[112:127], v[148:151], v[132:135], v[112:127]
	v_mfma_f32_32x32x16_bf16 v[96:111], v[148:151], v[128:131], v[96:111]
	v_mfma_f32_32x32x16_bf16 v[80:95], v[144:147], v[132:135], v[80:95]
	v_mfma_f32_32x32x16_bf16 v[64:79], v[144:147], v[128:131], v[64:79]
	v_mfma_f32_32x32x16_bf16 v[48:63], v[140:143], v[132:135], v[48:63]
	v_mfma_f32_32x32x16_bf16 v[32:47], v[140:143], v[128:131], v[32:47]
	v_mfma_f32_32x32x16_bf16 v[16:31], v[136:139], v[132:135], v[16:31]
	v_mfma_f32_32x32x16_bf16 v[0:15], v[136:139], v[128:131], v[0:15]
	s_cmp_gt_i32 s19, 0x17fff
	s_cselect_b32 s8, s27, 0x8000
	s_add_i32 s19, s8, s19
	s_add_i32 s18, s18, 1
	s_add_u32 s6, s6, 64
	s_barrier
	s_addc_u32 s7, s7, 0
	s_cmpk_eq_i32 s6, 0x1600
	s_cbranch_scc1 .LBB0_104
	s_branch .LBB0_98
.Lgkd_nodma:
	s_cmpk_gt_u32 s18, 0x55
	s_mov_b64 s[8:9], -1
	s_cbranch_scc0 .LBB0_100
	s_waitcnt vmcnt(0) lgkmcnt(0)
	s_barrier
	s_mov_b64 s[8:9], 0
.LBB0_100:
	s_andn2_b64 vcc, exec, s[8:9]
	s_cbranch_vccnz .LBB0_102
	s_waitcnt vmcnt(4) lgkmcnt(0)
	s_barrier
	s_branch .LBB0_102

.LBB0_123:
	v_or_b32_e32 v128, s18, v199
	v_add_u32_e32 v129, v128, v192
	ds_read_b128 v[156:159], v129 offset:0
	ds_read_b128 v[152:155], v129 offset:0x800
	v_add_u32_e32 v129, s18, v198
	ds_read_b128 v[172:175], v129 offset:0
	ds_read_b128 v[168:171], v129 offset:0x800
	ds_read_b128 v[164:167], v129 offset:0x1000
	ds_read_b128 v[160:163], v129 offset:0x1800
	v_add_u32_e32 v136, v128, v197
	ds_read_b128 v[132:135], v136 offset:0
	ds_read_b128 v[128:131], v136 offset:0x800
	v_add_u32_e32 v201, s18, v200
	ds_read_b128 v[148:151], v201 offset:0
	ds_read_b128 v[144:147], v201 offset:0x800
	ds_read_b128 v[140:143], v201 offset:0x1000
	ds_read_b128 v[136:139], v201 offset:0x1800
	s_cmp_gt_u32 s17, 28
	s_cbranch_scc1 .Lgku_nodma
	s_cmpk_gt_i32 s18, 0x7fff
	s_cselect_b32 s6, s21, 0x18000
	s_add_i32 s6, s6, s18
	s_add_i32 s6, s15, s6
	v_lshl_add_u64 v[234:235], v[184:185], 0, s[4:5]
	s_mov_b32 m0, s6
	s_nop 0
	global_load_lds_dwordx4 v[234:235], off
	v_lshl_add_u64 v[234:235], v[182:183], 0, s[4:5]
	s_add_i32 m0, s6, 0x400
	s_nop 0
	global_load_lds_dwordx4 v[234:235], off
	s_add_i32 m0, s6, 0x4000
	v_lshl_add_u64 v[234:235], v[180:181], 0, s[4:5]
	global_load_lds_dwordx4 v[234:235], off
	v_lshl_add_u64 v[234:235], v[178:179], 0, s[4:5]
	s_add_i32 m0, s6, 0x4400
	s_nop 0
	global_load_lds_dwordx4 v[234:235], off
	s_waitcnt vmcnt(8) lgkmcnt(0)
	s_barrier
.LBB0_127:
	v_mfma_f32_32x32x16_bf16 v[112:127], v[172:175], v[156:159], v[112:127]
	v_mfma_f32_32x32x16_bf16 v[96:111], v[172:175], v[152:155], v[96:111]
	v_mfma_f32_32x32x16_bf16 v[80:95], v[168:171], v[156:159], v[80:95]
	v_mfma_f32_32x32x16_bf16 v[64:79], v[168:171], v[152:155], v[64:79]
	v_mfma_f32_32x32x16_bf16 v[48:63], v[164:167], v[156:159], v[48:63]
	v_mfma_f32_32x32x16_bf16 v[32:47], v[164:167], v[152:155], v[32:47]
	v_mfma_f32_32x32x16_bf16 v[16:31], v[160:163], v[156:159], v[16:31]
	v_mfma_f32_32x32x16_bf16 v[0:15], v[160:163], v[152:155], v[0:15]
	v_mfma_f32_32x32x16_bf16 v[112:127], v[148:151], v[132:135], v[112:127]
	v_mfma_f32_32x32x16_bf16 v[96:111], v[148:151], v[128:131], v[96:111]
	v_mfma_f32_32x32x16_bf16 v[80:95], v[144:147], v[132:135], v[80:95]
	v_mfma_f32_32x32x16_bf16 v[64:79], v[144:147], v[128:131], v[64:79]
	v_mfma_f32_32x32x16_bf16 v[48:63], v[140:143], v[132:135], v[48:63]
	v_mfma_f32_32x32x16_bf16 v[32:47], v[140:143], v[128:131], v[32:47]
	v_mfma_f32_32x32x16_bf16 v[16:31], v[136:139], v[132:135], v[16:31]
	v_mfma_f32_32x32x16_bf16 v[0:15], v[136:139], v[128:131], v[0:15]
	s_cmp_gt_i32 s18, 0x17fff
	s_cselect_b32 s6, s27, 0x8000
	s_add_i32 s18, s6, s18
	s_add_i32 s17, s17, 1
	s_add_u32 s4, s4, 64
	s_barrier
	s_addc_u32 s5, s5, 0
	s_cmpk_eq_i32 s4, 0x800
	s_cbranch_scc1 .LBB0_129
	s_branch .LBB0_123
.Lgku_nodma:
	s_cmp_gt_u32 s17, 29
	s_mov_b64 s[6:7], -1
	s_cbranch_scc0 .LBB0_125
	s_waitcnt vmcnt(0) lgkmcnt(0)
	s_barrier
	s_mov_b64 s[6:7], 0
.LBB0_125:
	s_andn2_b64 vcc, exec, s[6:7]
	s_cbranch_vccnz .LBB0_127
	s_waitcnt vmcnt(4) lgkmcnt(0)
	s_barrier
	s_branch .LBB0_127

.LBB0_135:
	s_or_b64 exec, exec, s[4:5]
	v_or_b32_e32 v144, s12, v188
	v_ashrrev_i32_e32 v145, 31, v144
	v_readlane_b32 s2, v253, 30
	v_lshlrev_b64 v[142:143], 2, v[144:145]
	v_readlane_b32 s3, v253, 31
	v_lshl_add_u64 v[128:129], s[42:43], 0, v[142:143]
	v_lshl_add_u64 v[130:131], s[46:47], 0, v[142:143]
	v_lshl_add_u64 v[132:133], s[48:49], 0, v[142:143]
	v_lshl_add_u64 v[134:135], s[44:45], 0, v[142:143]
	v_lshl_add_u64 v[136:137], s[50:51], 0, v[142:143]
	v_lshl_add_u64 v[138:139], s[52:53], 0, v[142:143]
	v_lshl_add_u64 v[140:141], s[54:55], 0, v[142:143]
	v_lshl_add_u64 v[142:143], s[56:57], 0, v[142:143]
	v_lshl_add_u64 v[144:145], v[144:145], 1, s[2:3]
	global_load_dwordx4 v[208:211], v[128:129], off
	global_load_dwordx4 v[212:215], v[130:131], off
	global_load_dwordx4 v[216:219], v[132:133], off
	global_load_dwordx4 v[220:223], v[134:135], off
	global_load_dwordx4 v[224:227], v[136:137], off
	global_load_dwordx4 v[232:235], v[138:139], off
	global_load_dwordx4 v[244:247], v[140:141], off
	global_load_dwordx4 v[248:251], v[142:143], off
	global_load_dwordx4 v[178:181], v[136:137], off offset:16
	s_nop 0
	global_load_dwordx4 v[182:185], v[138:139], off offset:16
	s_nop 0
	global_load_dwordx4 v[198:201], v[140:141], off offset:16
	s_nop 0
	global_load_dwordx4 v[204:207], v[142:143], off offset:16
	s_nop 0
	global_load_dwordx4 v[136:139], v[128:129], off offset:16
	s_nop 0
	global_load_dwordx4 v[140:143], v[130:131], off offset:16
	s_nop 0
	global_load_dwordx4 v[128:131], v[132:133], off offset:16
	s_nop 0
	global_load_dwordx4 v[132:135], v[134:135], off offset:16
	s_nop 0
	s_mov_b32 s12, 0
	s_waitcnt vmcnt(0) lgkmcnt(0)
	s_barrier
	s_branch .LBB0_137

.LBB0_139:
	v_lshl_add_u32 v151, s36, 2, v150
	ds_read_b128 v[158:161], v151
	ds_read_b128 v[162:165], v151 offset:1040
	ds_read_b128 v[166:169], v151 offset:2080
	s_waitcnt lgkmcnt(2)
	v_pk_mul_f32 v[160:161], v[160:161], v[210:211]
	v_pk_mul_f32 v[158:159], v[158:159], v[208:209]
	s_waitcnt lgkmcnt(1)
	v_pk_mul_f32 v[164:165], v[164:165], v[214:215]
	v_pk_mul_f32 v[162:163], v[162:163], v[212:213]
	v_pk_fma_f32 v[160:161], v[152:153], v[160:161], v[164:165]
	v_pk_fma_f32 v[158:159], v[146:147], v[158:159], v[162:163]
	s_waitcnt lgkmcnt(0)
	v_pk_mul_f32 v[162:163], v[168:169], v[218:219]
	v_pk_mul_f32 v[164:165], v[166:167], v[216:217]
	v_pk_fma_f32 v[160:161], v[154:155], v[162:163], v[160:161]
	v_pk_fma_f32 v[162:163], v[148:149], v[164:165], v[158:159]
	v_pk_add_f32 v[158:159], v[222:223], v[160:161]
	v_pk_add_f32 v[160:161], v[220:221], v[162:163]
	ds_read_b128 v[162:165], v151 offset:512
	ds_read_b128 v[166:169], v151 offset:1552
	ds_read_b128 v[170:173], v151 offset:2592
	s_waitcnt lgkmcnt(2)
	v_pk_mul_f32 v[164:165], v[164:165], v[226:227]
	v_pk_mul_f32 v[162:163], v[162:163], v[224:225]
	s_waitcnt lgkmcnt(1)
	v_pk_mul_f32 v[168:169], v[168:169], v[234:235]
	v_pk_mul_f32 v[166:167], v[166:167], v[232:233]
	v_pk_fma_f32 v[164:165], v[152:153], v[164:165], v[168:169]
	v_pk_fma_f32 v[162:163], v[146:147], v[162:163], v[166:167]
	s_waitcnt lgkmcnt(0)
	v_pk_mul_f32 v[166:167], v[172:173], v[246:247]
	v_pk_mul_f32 v[168:169], v[170:171], v[244:245]
	v_pk_fma_f32 v[164:165], v[154:155], v[166:167], v[164:165]
	v_pk_fma_f32 v[166:167], v[148:149], v[168:169], v[162:163]
	v_pk_add_f32 v[162:163], v[250:251], v[164:165]
	v_pk_add_f32 v[164:165], v[248:249], v[166:167]
	v_mov_b64_e32 v[170:171], s[74:75]
	v_fma_f32 v151, |v164|, s1, 1.0
	v_rcp_f32_e32 v166, v151
	v_mul_f32_e32 v151, v164, v164
	v_mul_f32_e32 v151, 0xbf38aa3b, v151
	v_exp_f32_e32 v168, v151
	v_fma_f32 v151, |v165|, s1, 1.0
	v_rcp_f32_e32 v167, v151
	v_mul_f32_e32 v151, v165, v165
	v_mul_f32_e32 v151, 0xbf38aa3b, v151
	v_exp_f32_e32 v169, v151
	v_pk_fma_f32 v[172:173], v[166:167], s[22:23], v[170:171] op_sel_hi:[1,0,0]
	v_cmp_gt_f32_e32 vcc, 0, v164
	v_pk_fma_f32 v[172:173], v[166:167], v[172:173], s[24:25] op_sel_hi:[1,1,0]
	v_cmp_gt_f32_e64 s[38:39], 0, v165
	v_pk_fma_f32 v[172:173], v[166:167], v[172:173], s[26:27] op_sel_hi:[1,1,0]
	v_fma_f32 v151, |v162|, s1, 1.0
	v_pk_fma_f32 v[172:173], v[166:167], v[172:173], s[0:1] op_sel_hi:[1,1,0]
	s_nop 0
	v_pk_mul_f32 v[166:167], v[166:167], v[172:173]
	s_nop 0
	v_pk_mul_f32 v[166:167], v[168:169], v[166:167]
	s_nop 0
	v_pk_mul_f32 v[168:169], v[164:165], v[166:167]
	v_pk_fma_f32 v[164:165], v[164:165], v[166:167], v[164:165] neg_lo:[1,0,0] neg_hi:[1,0,0]
	s_nop 0
	v_cndmask_b32_e64 v165, v165, v169, s[38:39]
	v_cndmask_b32_e32 v164, v164, v168, vcc
	v_pk_mul_f32 v[160:161], v[160:161], v[164:165]
	v_rcp_f32_e32 v164, v151
	v_mul_f32_e32 v151, v162, v162
	v_mul_f32_e32 v151, 0xbf38aa3b, v151
	v_exp_f32_e32 v166, v151
	v_fma_f32 v151, |v163|, s1, 1.0
	v_rcp_f32_e32 v165, v151
	v_mul_f32_e32 v151, v163, v163
	v_mul_f32_e32 v151, 0xbf38aa3b, v151
	v_exp_f32_e32 v167, v151
	v_pk_fma_f32 v[168:169], v[164:165], s[22:23], v[170:171] op_sel_hi:[1,0,0]
	v_cmp_gt_f32_e32 vcc, 0, v162
	v_pk_fma_f32 v[168:169], v[164:165], v[168:169], s[24:25] op_sel_hi:[1,1,0]
	v_cmp_gt_f32_e64 s[38:39], 0, v163
	v_pk_fma_f32 v[168:169], v[164:165], v[168:169], s[26:27] op_sel_hi:[1,1,0]
	v_cvt_pk_bf16_f32 v160, v160, v161
	v_pk_fma_f32 v[168:169], v[164:165], v[168:169], s[0:1] op_sel_hi:[1,1,0]
	s_nop 0
	v_pk_mul_f32 v[164:165], v[164:165], v[168:169]
	s_nop 0
	v_pk_mul_f32 v[164:165], v[166:167], v[164:165]
	s_nop 0
	v_pk_mul_f32 v[166:167], v[162:163], v[164:165]
	v_pk_fma_f32 v[162:163], v[162:163], v[164:165], v[162:163] neg_lo:[1,0,0] neg_hi:[1,0,0]
	s_nop 0
	v_cndmask_b32_e64 v163, v163, v167, s[38:39]
	v_cndmask_b32_e32 v162, v162, v166, vcc
	v_pk_mul_f32 v[158:159], v[158:159], v[162:163]
	v_cvt_pk_bf16_f32 v161, v158, v159
	v_lshl_add_u64 v[158:159], s[36:37], 1, v[156:157]
	global_store_dwordx2 v[158:159], v[160:161], off
	s_nop 1
	s_mov_b32 s36, 4
	v_lshl_add_u32 v151, s36, 2, v150
	ds_read_b128 v[158:161], v151
	ds_read_b128 v[162:165], v151 offset:1040
	ds_read_b128 v[166:169], v151 offset:2080
	s_waitcnt lgkmcnt(2)
	v_pk_mul_f32 v[160:161], v[160:161], v[138:139]
	v_pk_mul_f32 v[158:159], v[158:159], v[136:137]
	s_waitcnt lgkmcnt(1)
	v_pk_mul_f32 v[164:165], v[164:165], v[142:143]
	v_pk_mul_f32 v[162:163], v[162:163], v[140:141]
	v_pk_fma_f32 v[160:161], v[152:153], v[160:161], v[164:165]
	v_pk_fma_f32 v[158:159], v[146:147], v[158:159], v[162:163]
	s_waitcnt lgkmcnt(0)
	v_pk_mul_f32 v[162:163], v[168:169], v[130:131]
	v_pk_mul_f32 v[164:165], v[166:167], v[128:129]
	v_pk_fma_f32 v[160:161], v[154:155], v[162:163], v[160:161]
	v_pk_fma_f32 v[162:163], v[148:149], v[164:165], v[158:159]
	v_pk_add_f32 v[158:159], v[134:135], v[160:161]
	v_pk_add_f32 v[160:161], v[132:133], v[162:163]
	ds_read_b128 v[162:165], v151 offset:512
	ds_read_b128 v[166:169], v151 offset:1552
	ds_read_b128 v[170:173], v151 offset:2592
	s_waitcnt lgkmcnt(2)
	v_pk_mul_f32 v[164:165], v[164:165], v[180:181]
	v_pk_mul_f32 v[162:163], v[162:163], v[178:179]
	s_waitcnt lgkmcnt(1)
	v_pk_mul_f32 v[168:169], v[168:169], v[184:185]
	v_pk_mul_f32 v[166:167], v[166:167], v[182:183]
	v_pk_fma_f32 v[164:165], v[152:153], v[164:165], v[168:169]
	v_pk_fma_f32 v[162:163], v[146:147], v[162:163], v[166:167]
	s_waitcnt lgkmcnt(0)
	v_pk_mul_f32 v[166:167], v[172:173], v[200:201]
	v_pk_mul_f32 v[168:169], v[170:171], v[198:199]
	v_pk_fma_f32 v[164:165], v[154:155], v[166:167], v[164:165]
	v_pk_fma_f32 v[166:167], v[148:149], v[168:169], v[162:163]
	v_pk_add_f32 v[162:163], v[206:207], v[164:165]
	v_pk_add_f32 v[164:165], v[204:205], v[166:167]
	v_mov_b64_e32 v[170:171], s[74:75]
	v_fma_f32 v151, |v164|, s1, 1.0
	v_rcp_f32_e32 v166, v151
	v_mul_f32_e32 v151, v164, v164
	v_mul_f32_e32 v151, 0xbf38aa3b, v151
	v_exp_f32_e32 v168, v151
	v_fma_f32 v151, |v165|, s1, 1.0
	v_rcp_f32_e32 v167, v151
	v_mul_f32_e32 v151, v165, v165
	v_mul_f32_e32 v151, 0xbf38aa3b, v151
	v_exp_f32_e32 v169, v151
	v_pk_fma_f32 v[172:173], v[166:167], s[22:23], v[170:171] op_sel_hi:[1,0,0]
	v_cmp_gt_f32_e32 vcc, 0, v164
	v_pk_fma_f32 v[172:173], v[166:167], v[172:173], s[24:25] op_sel_hi:[1,1,0]
	v_cmp_gt_f32_e64 s[38:39], 0, v165
	v_pk_fma_f32 v[172:173], v[166:167], v[172:173], s[26:27] op_sel_hi:[1,1,0]
	v_fma_f32 v151, |v162|, s1, 1.0
	v_pk_fma_f32 v[172:173], v[166:167], v[172:173], s[0:1] op_sel_hi:[1,1,0]
	s_nop 0
	v_pk_mul_f32 v[166:167], v[166:167], v[172:173]
	s_nop 0
	v_pk_mul_f32 v[166:167], v[168:169], v[166:167]
	s_nop 0
	v_pk_mul_f32 v[168:169], v[164:165], v[166:167]
	v_pk_fma_f32 v[164:165], v[164:165], v[166:167], v[164:165] neg_lo:[1,0,0] neg_hi:[1,0,0]
	s_nop 0
	v_cndmask_b32_e64 v165, v165, v169, s[38:39]
	v_cndmask_b32_e32 v164, v164, v168, vcc
	v_pk_mul_f32 v[160:161], v[160:161], v[164:165]
	v_rcp_f32_e32 v164, v151
	v_mul_f32_e32 v151, v162, v162
	v_mul_f32_e32 v151, 0xbf38aa3b, v151
	v_exp_f32_e32 v166, v151
	v_fma_f32 v151, |v163|, s1, 1.0
	v_rcp_f32_e32 v165, v151
	v_mul_f32_e32 v151, v163, v163
	v_mul_f32_e32 v151, 0xbf38aa3b, v151
	v_exp_f32_e32 v167, v151
	v_pk_fma_f32 v[168:169], v[164:165], s[22:23], v[170:171] op_sel_hi:[1,0,0]
	v_cmp_gt_f32_e32 vcc, 0, v162
	v_pk_fma_f32 v[168:169], v[164:165], v[168:169], s[24:25] op_sel_hi:[1,1,0]
	v_cmp_gt_f32_e64 s[38:39], 0, v163
	v_pk_fma_f32 v[168:169], v[164:165], v[168:169], s[26:27] op_sel_hi:[1,1,0]
	v_cvt_pk_bf16_f32 v160, v160, v161
	v_pk_fma_f32 v[168:169], v[164:165], v[168:169], s[0:1] op_sel_hi:[1,1,0]
	s_nop 0
	v_pk_mul_f32 v[164:165], v[164:165], v[168:169]
	s_nop 0
	v_pk_mul_f32 v[164:165], v[166:167], v[164:165]
	s_nop 0
	v_pk_mul_f32 v[166:167], v[162:163], v[164:165]
	v_pk_fma_f32 v[162:163], v[162:163], v[164:165], v[162:163] neg_lo:[1,0,0] neg_hi:[1,0,0]
	s_nop 0
	v_cndmask_b32_e64 v163, v163, v167, s[38:39]
	v_cndmask_b32_e32 v162, v162, v166, vcc
	v_pk_mul_f32 v[158:159], v[158:159], v[162:163]
	v_cvt_pk_bf16_f32 v161, v158, v159
	v_lshl_add_u64 v[158:159], s[36:37], 1, v[156:157]
	global_store_dwordx2 v[158:159], v[160:161], off
	s_branch .LBB0_136

.LBB0_148:
	s_lshl_b32 s13, s36, 2
	v_add_u32_e32 v40, s13, v18
	v_add_u32_e32 v41, s13, v19
	ds_read_b128 v[10:13], v40
	ds_read_b128 v[14:17], v41
	ds_read_b128 v[20:23], v40 offset:2080
	s_waitcnt lgkmcnt(2)
	v_pk_mul_f32 v[12:13], v[12:13], v[210:211]
	v_pk_mul_f32 v[10:11], v[10:11], v[208:209]
	s_waitcnt lgkmcnt(1)
	v_pk_mul_f32 v[16:17], v[16:17], v[214:215]
	v_pk_mul_f32 v[14:15], v[14:15], v[212:213]
	v_pk_fma_f32 v[12:13], v[4:5], v[12:13], v[16:17]
	v_pk_fma_f32 v[10:11], v[0:1], v[10:11], v[14:15]
	s_waitcnt lgkmcnt(0)
	v_pk_mul_f32 v[14:15], v[22:23], v[218:219]
	v_pk_mul_f32 v[16:17], v[20:21], v[216:217]
	v_pk_fma_f32 v[12:13], v[6:7], v[14:15], v[12:13]
	v_pk_fma_f32 v[14:15], v[2:3], v[16:17], v[10:11]
	v_pk_add_f32 v[10:11], v[222:223], v[12:13]
	v_pk_add_f32 v[12:13], v[220:221], v[14:15]
	ds_read_b128 v[14:17], v40 offset:512
	ds_read_b128 v[20:23], v41 offset:512
	ds_read_b128 v[24:27], v40 offset:2592
	s_waitcnt lgkmcnt(2)
	v_pk_mul_f32 v[16:17], v[16:17], v[226:227]
	v_pk_mul_f32 v[14:15], v[14:15], v[224:225]
	s_waitcnt lgkmcnt(1)
	v_pk_mul_f32 v[22:23], v[22:23], v[234:235]
	v_pk_mul_f32 v[20:21], v[20:21], v[232:233]
	v_pk_fma_f32 v[16:17], v[4:5], v[16:17], v[22:23]
	v_pk_fma_f32 v[14:15], v[0:1], v[14:15], v[20:21]
	s_waitcnt lgkmcnt(0)
	v_pk_mul_f32 v[20:21], v[26:27], v[246:247]
	v_pk_mul_f32 v[22:23], v[24:25], v[244:245]
	v_pk_fma_f32 v[16:17], v[6:7], v[20:21], v[16:17]
	v_pk_fma_f32 v[20:21], v[2:3], v[22:23], v[14:15]
	v_mov_b64_e32 v[24:25], s[74:75]
	v_pk_add_f32 v[14:15], v[250:251], v[16:17]
	v_pk_add_f32 v[16:17], v[248:249], v[20:21]
	s_nop 0
	v_mul_f32_e32 v21, v16, v16
	v_mul_f32_e32 v21, 0xbf38aa3b, v21
	v_fma_f32 v20, |v16|, s1, 1.0
	v_exp_f32_e32 v22, v21
	v_fma_f32 v21, |v17|, s1, 1.0
	v_rcp_f32_e32 v20, v20
	v_rcp_f32_e32 v21, v21
	v_mul_f32_e32 v23, v17, v17
	v_mul_f32_e32 v23, 0xbf38aa3b, v23
	v_exp_f32_e32 v23, v23
	v_pk_fma_f32 v[26:27], v[20:21], s[22:23], v[24:25] op_sel_hi:[1,0,0]
	v_cmp_gt_f32_e32 vcc, 0, v16
	v_pk_fma_f32 v[26:27], v[20:21], v[26:27], s[24:25] op_sel_hi:[1,1,0]
	v_cmp_gt_f32_e64 s[38:39], 0, v17
	v_pk_fma_f32 v[26:27], v[20:21], v[26:27], s[26:27] op_sel_hi:[1,1,0]
	s_nop 0
	v_pk_fma_f32 v[26:27], v[20:21], v[26:27], s[0:1] op_sel_hi:[1,1,0]
	s_nop 0
	v_pk_mul_f32 v[20:21], v[20:21], v[26:27]
	s_nop 0
	v_pk_mul_f32 v[20:21], v[22:23], v[20:21]
	s_nop 0
	v_pk_mul_f32 v[22:23], v[16:17], v[20:21]
	v_pk_fma_f32 v[16:17], v[16:17], v[20:21], v[16:17] neg_lo:[1,0,0] neg_hi:[1,0,0]
	s_nop 0
	v_cndmask_b32_e64 v17, v17, v23, s[38:39]
	v_cndmask_b32_e32 v16, v16, v22, vcc
	v_pk_mul_f32 v[12:13], v[12:13], v[16:17]
	v_cmp_gt_f32_e32 vcc, 0, v14
	v_cvt_pk_bf16_f32 v12, v12, v13
	v_fma_f32 v13, |v14|, s1, 1.0
	v_rcp_f32_e32 v16, v13
	v_mul_f32_e32 v13, v14, v14
	v_mul_f32_e32 v13, 0xbf38aa3b, v13
	v_exp_f32_e32 v20, v13
	v_fma_f32 v13, |v15|, s1, 1.0
	v_rcp_f32_e32 v17, v13
	v_mul_f32_e32 v13, v15, v15
	v_mul_f32_e32 v13, 0xbf38aa3b, v13
	v_exp_f32_e32 v21, v13
	v_pk_fma_f32 v[22:23], v[16:17], s[22:23], v[24:25] op_sel_hi:[1,0,0]
	v_cmp_gt_f32_e64 s[38:39], 0, v15
	v_pk_fma_f32 v[22:23], v[16:17], v[22:23], s[24:25] op_sel_hi:[1,1,0]
	s_nop 0
	v_pk_fma_f32 v[22:23], v[16:17], v[22:23], s[26:27] op_sel_hi:[1,1,0]
	s_nop 0
	v_pk_fma_f32 v[22:23], v[16:17], v[22:23], s[0:1] op_sel_hi:[1,1,0]
	s_nop 0
	v_pk_mul_f32 v[16:17], v[16:17], v[22:23]
	s_nop 0
	v_pk_mul_f32 v[16:17], v[20:21], v[16:17]
	s_nop 0
	v_pk_mul_f32 v[20:21], v[14:15], v[16:17]
	v_pk_fma_f32 v[14:15], v[14:15], v[16:17], v[14:15] neg_lo:[1,0,0] neg_hi:[1,0,0]
	s_nop 0
	v_cndmask_b32_e64 v15, v15, v21, s[38:39]
	v_cndmask_b32_e32 v14, v14, v20, vcc
	v_pk_mul_f32 v[10:11], v[10:11], v[14:15]
	v_cvt_pk_bf16_f32 v13, v10, v11
	v_lshl_add_u64 v[10:11], s[36:37], 1, v[8:9]
	global_store_dwordx2 v[10:11], v[12:13], off
	s_nop 1
	s_mov_b32 s36, 4
	s_lshl_b32 s13, s36, 2
	v_add_u32_e32 v40, s13, v18
	v_add_u32_e32 v41, s13, v19
	ds_read_b128 v[10:13], v40
	ds_read_b128 v[14:17], v41
	ds_read_b128 v[20:23], v40 offset:2080
	s_waitcnt lgkmcnt(2)
	v_pk_mul_f32 v[12:13], v[12:13], v[138:139]
	v_pk_mul_f32 v[10:11], v[10:11], v[136:137]
	s_waitcnt lgkmcnt(1)
	v_pk_mul_f32 v[16:17], v[16:17], v[142:143]
	v_pk_mul_f32 v[14:15], v[14:15], v[140:141]
	v_pk_fma_f32 v[12:13], v[4:5], v[12:13], v[16:17]
	v_pk_fma_f32 v[10:11], v[0:1], v[10:11], v[14:15]
	s_waitcnt lgkmcnt(0)
	v_pk_mul_f32 v[14:15], v[22:23], v[130:131]
	v_pk_mul_f32 v[16:17], v[20:21], v[128:129]
	v_pk_fma_f32 v[12:13], v[6:7], v[14:15], v[12:13]
	v_pk_fma_f32 v[14:15], v[2:3], v[16:17], v[10:11]
	v_pk_add_f32 v[10:11], v[134:135], v[12:13]
	v_pk_add_f32 v[12:13], v[132:133], v[14:15]
	ds_read_b128 v[14:17], v40 offset:512
	ds_read_b128 v[20:23], v41 offset:512
	ds_read_b128 v[24:27], v40 offset:2592
	s_waitcnt lgkmcnt(2)
	v_pk_mul_f32 v[16:17], v[16:17], v[180:181]
	v_pk_mul_f32 v[14:15], v[14:15], v[178:179]
	s_waitcnt lgkmcnt(1)
	v_pk_mul_f32 v[22:23], v[22:23], v[184:185]
	v_pk_mul_f32 v[20:21], v[20:21], v[182:183]
	v_pk_fma_f32 v[16:17], v[4:5], v[16:17], v[22:23]
	v_pk_fma_f32 v[14:15], v[0:1], v[14:15], v[20:21]
	s_waitcnt lgkmcnt(0)
	v_pk_mul_f32 v[20:21], v[26:27], v[200:201]
	v_pk_mul_f32 v[22:23], v[24:25], v[198:199]
	v_pk_fma_f32 v[16:17], v[6:7], v[20:21], v[16:17]
	v_pk_fma_f32 v[20:21], v[2:3], v[22:23], v[14:15]
	v_mov_b64_e32 v[24:25], s[74:75]
	v_pk_add_f32 v[14:15], v[206:207], v[16:17]
	v_pk_add_f32 v[16:17], v[204:205], v[20:21]
	s_nop 0
	v_mul_f32_e32 v21, v16, v16
	v_mul_f32_e32 v21, 0xbf38aa3b, v21
	v_fma_f32 v20, |v16|, s1, 1.0
	v_exp_f32_e32 v22, v21
	v_fma_f32 v21, |v17|, s1, 1.0
	v_rcp_f32_e32 v20, v20
	v_rcp_f32_e32 v21, v21
	v_mul_f32_e32 v23, v17, v17
	v_mul_f32_e32 v23, 0xbf38aa3b, v23
	v_exp_f32_e32 v23, v23
	v_pk_fma_f32 v[26:27], v[20:21], s[22:23], v[24:25] op_sel_hi:[1,0,0]
	v_cmp_gt_f32_e32 vcc, 0, v16
	v_pk_fma_f32 v[26:27], v[20:21], v[26:27], s[24:25] op_sel_hi:[1,1,0]
	v_cmp_gt_f32_e64 s[38:39], 0, v17
	v_pk_fma_f32 v[26:27], v[20:21], v[26:27], s[26:27] op_sel_hi:[1,1,0]
	s_nop 0
	v_pk_fma_f32 v[26:27], v[20:21], v[26:27], s[0:1] op_sel_hi:[1,1,0]
	s_nop 0
	v_pk_mul_f32 v[20:21], v[20:21], v[26:27]
	s_nop 0
	v_pk_mul_f32 v[20:21], v[22:23], v[20:21]
	s_nop 0
	v_pk_mul_f32 v[22:23], v[16:17], v[20:21]
	v_pk_fma_f32 v[16:17], v[16:17], v[20:21], v[16:17] neg_lo:[1,0,0] neg_hi:[1,0,0]
	s_nop 0
	v_cndmask_b32_e64 v17, v17, v23, s[38:39]
	v_cndmask_b32_e32 v16, v16, v22, vcc
	v_pk_mul_f32 v[12:13], v[12:13], v[16:17]
	v_cmp_gt_f32_e32 vcc, 0, v14
	v_cvt_pk_bf16_f32 v12, v12, v13
	v_fma_f32 v13, |v14|, s1, 1.0
	v_rcp_f32_e32 v16, v13
	v_mul_f32_e32 v13, v14, v14
	v_mul_f32_e32 v13, 0xbf38aa3b, v13
	v_exp_f32_e32 v20, v13
	v_fma_f32 v13, |v15|, s1, 1.0
	v_rcp_f32_e32 v17, v13
	v_mul_f32_e32 v13, v15, v15
	v_mul_f32_e32 v13, 0xbf38aa3b, v13
	v_exp_f32_e32 v21, v13
	v_pk_fma_f32 v[22:23], v[16:17], s[22:23], v[24:25] op_sel_hi:[1,0,0]
	v_cmp_gt_f32_e64 s[38:39], 0, v15
	v_pk_fma_f32 v[22:23], v[16:17], v[22:23], s[24:25] op_sel_hi:[1,1,0]
	s_nop 0
	v_pk_fma_f32 v[22:23], v[16:17], v[22:23], s[26:27] op_sel_hi:[1,1,0]
	s_nop 0
	v_pk_fma_f32 v[22:23], v[16:17], v[22:23], s[0:1] op_sel_hi:[1,1,0]
	s_nop 0
	v_pk_mul_f32 v[16:17], v[16:17], v[22:23]
	s_nop 0
	v_pk_mul_f32 v[16:17], v[20:21], v[16:17]
	s_nop 0
	v_pk_mul_f32 v[20:21], v[14:15], v[16:17]
	v_pk_fma_f32 v[14:15], v[14:15], v[16:17], v[14:15] neg_lo:[1,0,0] neg_hi:[1,0,0]
	s_nop 0
	v_cndmask_b32_e64 v15, v15, v21, s[38:39]
	v_cndmask_b32_e32 v14, v14, v20, vcc
	v_pk_mul_f32 v[10:11], v[10:11], v[14:15]
	v_cvt_pk_bf16_f32 v13, v10, v11
	v_lshl_add_u64 v[10:11], s[36:37], 1, v[8:9]
	global_store_dwordx2 v[10:11], v[12:13], off
	s_branch .LBB0_145

.LBB0_171:
	v_or_b32_e32 v128, s18, v212
	v_add_u32_e32 v129, v128, v203
	ds_read_b128 v[156:159], v129 offset:0
	ds_read_b128 v[152:155], v129 offset:0x800
	v_add_u32_e32 v129, s18, v211
	ds_read_b128 v[172:175], v129 offset:0
	ds_read_b128 v[168:171], v129 offset:0x800
	ds_read_b128 v[164:167], v129 offset:0x1000
	ds_read_b128 v[160:163], v129 offset:0x1800
	v_add_u32_e32 v136, v128, v204
	ds_read_b128 v[132:135], v136 offset:0
	ds_read_b128 v[128:131], v136 offset:0x800
	v_add_u32_e32 v176, s18, v214
	ds_read_b128 v[148:151], v176 offset:0
	ds_read_b128 v[144:147], v176 offset:0x800
	ds_read_b128 v[140:143], v176 offset:0x1000
	ds_read_b128 v[136:139], v176 offset:0x1800
	s_cmp_gt_u32 s17, 28
	s_cbranch_scc1 .Lgko_nodma
	s_cmpk_gt_i32 s18, 0x7fff
	s_cselect_b32 s6, s19, 0x18000
	s_add_i32 s6, s6, s18
	s_add_i32 s6, s15, s6
	v_lshl_add_u64 v[234:235], v[188:189], 0, s[4:5]
	s_mov_b32 m0, s6
	s_nop 0
	global_load_lds_dwordx4 v[234:235], off
	v_lshl_add_u64 v[234:235], v[186:187], 0, s[4:5]
	s_add_i32 m0, s6, 0x400
	s_nop 0
	global_load_lds_dwordx4 v[234:235], off
	s_add_i32 m0, s6, 0x4000
	v_lshl_add_u64 v[234:235], v[184:185], 0, s[4:5]
	global_load_lds_dwordx4 v[234:235], off
	v_lshl_add_u64 v[234:235], v[182:183], 0, s[4:5]
	s_add_i32 m0, s6, 0x4400
	s_nop 0
	global_load_lds_dwordx4 v[234:235], off
	s_waitcnt vmcnt(8) lgkmcnt(0)
	s_barrier

.LBB0_295:
	v_or_b32_e32 v128, s29, v189
	v_add_u32_e32 v129, v128, v186
	ds_read_b128 v[156:159], v129 offset:0
	ds_read_b128 v[152:155], v129 offset:0x800
	v_add_u32_e32 v129, s29, v188
	ds_read_b128 v[172:175], v129 offset:0
	ds_read_b128 v[168:171], v129 offset:0x800
	ds_read_b128 v[164:167], v129 offset:0x1000
	ds_read_b128 v[160:163], v129 offset:0x1800
	v_add_u32_e32 v136, v128, v187
	ds_read_b128 v[132:135], v136 offset:0
	ds_read_b128 v[128:131], v136 offset:0x800
	v_add_u32_e32 v176, s29, v191
	ds_read_b128 v[148:151], v176 offset:0
	ds_read_b128 v[144:147], v176 offset:0x800
	ds_read_b128 v[140:143], v176 offset:0x1000
	ds_read_b128 v[136:139], v176 offset:0x1800
	s_cmp_gt_u32 s19, 28
	s_cbranch_scc1 .Lgkq_nodma
	s_cmpk_gt_i32 s29, 0x7fff
	s_cselect_b32 s6, s21, 0x18000
	s_add_i32 s6, s6, s29
	s_add_i32 s6, s18, s6
	v_lshl_add_u64 v[234:235], v[184:185], 0, s[4:5]
	s_mov_b32 m0, s6
	s_nop 0
	global_load_lds_dwordx4 v[234:235], off
	v_lshl_add_u64 v[234:235], v[182:183], 0, s[4:5]
	s_add_i32 m0, s6, 0x400
	s_nop 0
	global_load_lds_dwordx4 v[234:235], off
	s_add_i32 m0, s6, 0x4000
	v_lshl_add_u64 v[234:235], v[180:181], 0, s[4:5]
	global_load_lds_dwordx4 v[234:235], off
	v_lshl_add_u64 v[234:235], v[178:179], 0, s[4:5]
	s_add_i32 m0, s6, 0x4400
	s_nop 0
	global_load_lds_dwordx4 v[234:235], off
	s_waitcnt vmcnt(8) lgkmcnt(0)
	s_barrier
.LBB0_299:
	v_mfma_f32_32x32x16_bf16 v[112:127], v[172:175], v[156:159], v[112:127]
	v_mfma_f32_32x32x16_bf16 v[96:111], v[172:175], v[152:155], v[96:111]
	v_mfma_f32_32x32x16_bf16 v[80:95], v[168:171], v[156:159], v[80:95]
	v_mfma_f32_32x32x16_bf16 v[64:79], v[168:171], v[152:155], v[64:79]
	v_mfma_f32_32x32x16_bf16 v[48:63], v[164:167], v[156:159], v[48:63]
	v_mfma_f32_32x32x16_bf16 v[32:47], v[164:167], v[152:155], v[32:47]
	v_mfma_f32_32x32x16_bf16 v[16:31], v[160:163], v[156:159], v[16:31]
	v_mfma_f32_32x32x16_bf16 v[0:15], v[160:163], v[152:155], v[0:15]
	v_mfma_f32_32x32x16_bf16 v[112:127], v[148:151], v[132:135], v[112:127]
	v_mfma_f32_32x32x16_bf16 v[96:111], v[148:151], v[128:131], v[96:111]
	v_mfma_f32_32x32x16_bf16 v[80:95], v[144:147], v[132:135], v[80:95]
	v_mfma_f32_32x32x16_bf16 v[64:79], v[144:147], v[128:131], v[64:79]
	v_mfma_f32_32x32x16_bf16 v[48:63], v[140:143], v[132:135], v[48:63]
	v_mfma_f32_32x32x16_bf16 v[32:47], v[140:143], v[128:131], v[32:47]
	v_mfma_f32_32x32x16_bf16 v[16:31], v[136:139], v[132:135], v[16:31]
	v_mfma_f32_32x32x16_bf16 v[0:15], v[136:139], v[128:131], v[0:15]
	s_cmp_gt_i32 s29, 0x17fff
	s_cselect_b32 s6, s27, 0x8000
	s_add_i32 s29, s6, s29
	s_add_i32 s19, s19, 1
	s_add_u32 s4, s4, 64
	s_barrier
	s_addc_u32 s5, s5, 0
	s_cmpk_eq_i32 s4, 0x800
	s_cbranch_scc1 .LBB0_301
	s_branch .LBB0_295
.Lgkq_nodma:
	s_cmp_gt_u32 s19, 29
	s_mov_b64 s[6:7], -1
	s_cbranch_scc0 .LBB0_297
	s_waitcnt vmcnt(0) lgkmcnt(0)
	s_barrier
	s_mov_b64 s[6:7], 0

.LBB0_441:
	v_mov_b32_e32 v184, s28
	v_mov_b32_e32 v185, s28
	v_mov_b32_e32 v186, s28
	v_mov_b32_e32 v187, s28
	v_add_u32_e32 v173, v173, v174
	s_mov_b32 s29, s28
	s_mov_b32 s30, s28
	s_mov_b32 s31, s28
.Lat_d_top:
	ds_read_b128 v[64:67], v181 offset:0
	ds_read_b128 v[68:71], v181 offset:32
	ds_read_b128 v[72:75], v181 offset:64
	ds_read_b128 v[76:79], v181 offset:96
	s_cmp_gt_u32 s10, 61
	s_cbranch_scc1 .Lat_d_nold0
	v_lshl_add_u64 v[174:175], v[170:171], 0, v[176:177]
	v_add_co_u32_e32 v174, vcc, 0x18561000, v174
	s_nop 1
	v_addc_co_u32_e32 v175, vcc, 0, v175, vcc
	global_load_dwordx4 v[128:131], v[174:175], off offset:1024
	global_load_dwordx4 v[132:135], v[174:175], off offset:1280
	v_lshl_add_u64 v[174:175], v[168:169], 0, v[176:177]
	v_add_co_u32_e32 v174, vcc, 0x18401000, v174
	s_nop 1
	v_addc_co_u32_e32 v175, vcc, 0, v175, vcc
	global_load_dwordx4 v[136:139], v[174:175], off offset:1024
	global_load_dwordx4 v[140:143], v[174:175], off offset:1280
.Lat_d_nold0:
	s_waitcnt lgkmcnt(3)
	v_mfma_f32_32x32x16_bf16 v[80:95], v[64:67], v[120:123], v[48:63]
	ds_read_b128 v[64:67], v181 offset:4608
	s_waitcnt lgkmcnt(3)
	v_mfma_f32_32x32x16_bf16 v[80:95], v[68:71], v[112:115], v[80:95]
	ds_read_b128 v[68:71], v181 offset:4640
	s_waitcnt lgkmcnt(3)
	v_mfma_f32_32x32x16_bf16 v[80:95], v[72:75], v[116:119], v[80:95]
	ds_read_b128 v[72:75], v181 offset:4672
	s_waitcnt lgkmcnt(3)
	v_mfma_f32_32x32x16_bf16 v[80:95], v[76:79], v[124:127], v[80:95]
	ds_read_b128 v[76:79], v181 offset:4704
	s_waitcnt lgkmcnt(3)
	v_mfma_f32_32x32x16_bf16 v[96:111], v[64:67], v[120:123], v[48:63]
	s_waitcnt lgkmcnt(2)
	v_mfma_f32_32x32x16_bf16 v[96:111], v[68:71], v[112:115], v[96:111]
	s_waitcnt lgkmcnt(1)
	v_mfma_f32_32x32x16_bf16 v[96:111], v[72:75], v[116:119], v[96:111]
	s_waitcnt lgkmcnt(0)
	v_mfma_f32_32x32x16_bf16 v[96:111], v[76:79], v[124:127], v[96:111]
	ds_read_b64_tr_b16 v[64:65], v178 offset:9216
	ds_read_b64_tr_b16 v[66:67], v178 offset:9728
	ds_read_b64_tr_b16 v[68:69], v178 offset:13312
	ds_read_b64_tr_b16 v[70:71], v178 offset:13824
	ds_read_b64_tr_b16 v[72:73], v178 offset:10240
	ds_read_b64_tr_b16 v[74:75], v178 offset:10752
	ds_read_b64_tr_b16 v[76:77], v178 offset:14336
	ds_read_b64_tr_b16 v[78:79], v178 offset:14848
	v_max3_f32 v182, v80, v81, v82
	v_max3_f32 v183, v88, v89, v90
	v_max3_f32 v182, v182, v83, v84
	v_max3_f32 v183, v183, v91, v92
	v_max3_f32 v182, v182, v85, v86
	v_max3_f32 v183, v183, v93, v94
	v_max_f32_e32 v182, v182, v87
	v_max_f32_e32 v183, v183, v95
	v_max3_f32 v174, v96, v97, v98
	v_max3_f32 v175, v104, v105, v106
	v_max3_f32 v174, v174, v99, v100
	v_max3_f32 v175, v175, v107, v108
	v_max3_f32 v174, v174, v101, v102
	v_max3_f32 v175, v175, v109, v110
	v_max_f32_e32 v174, v174, v103
	v_max_f32_e32 v175, v175, v111
	v_max3_f32 v182, v182, v183, v174
	v_max_f32_e32 v182, v182, v175
	v_mov_b32_e32 v183, v182
	s_nop 1
	v_permlane32_swap_b32_e32 v182, v183
	v_max_f32_e32 v182, v182, v183
	v_cmp_lt_f32_e64 s[38:39], s23, v182
	v_cmp_lt_f32_e64 s[6:7], s75, v182
	s_andn2_b64 s[8:9], s[38:39], s[4:5]
	s_or_b64 s[4:5], s[4:5], s[38:39]
	s_or_b64 s[6:7], s[6:7], s[8:9]
	s_cbranch_scc1 .Lat_d0_rare
.Lat_d0_cont:
	v_exp_f32_e32 v80, v80
	v_exp_f32_e32 v81, v81
	v_exp_f32_e32 v82, v82
	v_exp_f32_e32 v83, v83
	v_exp_f32_e32 v84, v84
	v_exp_f32_e32 v85, v85
	v_exp_f32_e32 v86, v86
	v_exp_f32_e32 v87, v87
	v_cvt_pk_bf16_f32 v80, v80, v81
	v_cvt_pk_bf16_f32 v81, v82, v83
	v_cvt_pk_bf16_f32 v82, v84, v85
	v_cvt_pk_bf16_f32 v83, v86, v87
	ds_read_b64_tr_b16 v[84:85], v178 offset:11264
	ds_read_b64_tr_b16 v[86:87], v178 offset:11776
	s_waitcnt lgkmcnt(8)
	v_mfma_f32_32x32x16_bf16 v[16:31], v[64:67], v[80:83], v[16:31]
	v_exp_f32_e32 v88, v88
	v_exp_f32_e32 v89, v89
	v_exp_f32_e32 v90, v90
	s_waitcnt lgkmcnt(6)
	v_mfma_f32_32x32x16_bf16 v[0:15], v[68:71], v[80:83], v[0:15]
	v_exp_f32_e32 v91, v91
	v_exp_f32_e32 v92, v92
	v_exp_f32_e32 v93, v93
	v_mfma_f32_32x32x16_bf16 v[32:47], v[184:187], v[80:83], v[32:47]
	v_exp_f32_e32 v94, v94
	v_exp_f32_e32 v95, v95
	v_cvt_pk_bf16_f32 v88, v88, v89
	v_cvt_pk_bf16_f32 v89, v90, v91
	v_cvt_pk_bf16_f32 v90, v92, v93
	v_cvt_pk_bf16_f32 v91, v94, v95
	ds_read_b64_tr_b16 v[80:81], v178 offset:15360
	ds_read_b64_tr_b16 v[82:83], v178 offset:15872
	ds_read_b64_tr_b16 v[92:93], v178 offset:12288
	ds_read_b64_tr_b16 v[94:95], v178 offset:12800
	s_waitcnt lgkmcnt(8)
	v_mfma_f32_32x32x16_bf16 v[16:31], v[72:75], v[88:91], v[16:31]
	v_exp_f32_e32 v96, v96
	v_exp_f32_e32 v97, v97
	v_exp_f32_e32 v98, v98
	s_waitcnt lgkmcnt(6)
	v_mfma_f32_32x32x16_bf16 v[0:15], v[76:79], v[88:91], v[0:15]
	v_exp_f32_e32 v99, v99
	v_exp_f32_e32 v100, v100
	v_exp_f32_e32 v101, v101
	v_mfma_f32_32x32x16_bf16 v[32:47], v[184:187], v[88:91], v[32:47]
	v_exp_f32_e32 v102, v102
	v_exp_f32_e32 v103, v103
	v_cvt_pk_bf16_f32 v96, v96, v97
	v_cvt_pk_bf16_f32 v97, v98, v99
	v_cvt_pk_bf16_f32 v98, v100, v101
	v_cvt_pk_bf16_f32 v99, v102, v103
	ds_read_b64_tr_b16 v[88:89], v178 offset:16384
	ds_read_b64_tr_b16 v[90:91], v178 offset:16896
	ds_read_b128 v[64:67], v181 offset:17408
	ds_read_b128 v[68:71], v181 offset:17440
	ds_read_b128 v[72:75], v181 offset:17472
	ds_read_b128 v[76:79], v181 offset:17504
	s_waitcnt lgkmcnt(10)
	v_mfma_f32_32x32x16_bf16 v[16:31], v[84:87], v[96:99], v[16:31]
	v_exp_f32_e32 v104, v104
	v_exp_f32_e32 v105, v105
	v_exp_f32_e32 v106, v106
	s_waitcnt lgkmcnt(8)
	v_mfma_f32_32x32x16_bf16 v[0:15], v[80:83], v[96:99], v[0:15]
	v_exp_f32_e32 v107, v107
	v_exp_f32_e32 v108, v108
	v_exp_f32_e32 v109, v109
	v_mfma_f32_32x32x16_bf16 v[32:47], v[184:187], v[96:99], v[32:47]
	v_exp_f32_e32 v110, v110
	v_exp_f32_e32 v111, v111
	v_cvt_pk_bf16_f32 v104, v104, v105
	v_cvt_pk_bf16_f32 v105, v106, v107
	v_cvt_pk_bf16_f32 v106, v108, v109
	v_cvt_pk_bf16_f32 v107, v110, v111
	s_waitcnt lgkmcnt(6)
	s_nop 1
	v_mfma_f32_32x32x16_bf16 v[16:31], v[92:95], v[104:107], v[16:31]
	s_waitcnt lgkmcnt(4)
	v_mfma_f32_32x32x16_bf16 v[0:15], v[88:91], v[104:107], v[0:15]
	v_mfma_f32_32x32x16_bf16 v[32:47], v[184:187], v[104:107], v[32:47]
	s_waitcnt lgkmcnt(3)
	v_mfma_f32_32x32x16_bf16 v[80:95], v[64:67], v[120:123], v[48:63]
	ds_read_b128 v[64:67], v181 offset:22016
	s_waitcnt lgkmcnt(3)
	v_mfma_f32_32x32x16_bf16 v[80:95], v[68:71], v[112:115], v[80:95]
	ds_read_b128 v[68:71], v181 offset:22048
	s_waitcnt lgkmcnt(3)
	v_mfma_f32_32x32x16_bf16 v[80:95], v[72:75], v[116:119], v[80:95]
	ds_read_b128 v[72:75], v181 offset:22080
	s_waitcnt lgkmcnt(3)
	v_mfma_f32_32x32x16_bf16 v[80:95], v[76:79], v[124:127], v[80:95]
	ds_read_b128 v[76:79], v181 offset:22112
	s_waitcnt lgkmcnt(3)
	v_mfma_f32_32x32x16_bf16 v[96:111], v[64:67], v[120:123], v[48:63]
	s_waitcnt lgkmcnt(2)
	v_mfma_f32_32x32x16_bf16 v[96:111], v[68:71], v[112:115], v[96:111]
	s_waitcnt lgkmcnt(1)
	v_mfma_f32_32x32x16_bf16 v[96:111], v[72:75], v[116:119], v[96:111]
	s_waitcnt lgkmcnt(0)
	v_mfma_f32_32x32x16_bf16 v[96:111], v[76:79], v[124:127], v[96:111]
	ds_read_b64_tr_b16 v[64:65], v178 offset:26624
	ds_read_b64_tr_b16 v[66:67], v178 offset:27136
	ds_read_b64_tr_b16 v[68:69], v178 offset:30720
	ds_read_b64_tr_b16 v[70:71], v178 offset:31232
	ds_read_b64_tr_b16 v[72:73], v178 offset:27648
	ds_read_b64_tr_b16 v[74:75], v178 offset:28160
	ds_read_b64_tr_b16 v[76:77], v178 offset:31744
	ds_read_b64_tr_b16 v[78:79], v178 offset:32256
	v_max3_f32 v182, v80, v81, v82
	v_max3_f32 v183, v88, v89, v90
	v_max3_f32 v182, v182, v83, v84
	v_max3_f32 v183, v183, v91, v92
	v_max3_f32 v182, v182, v85, v86
	v_max3_f32 v183, v183, v93, v94
	v_max_f32_e32 v182, v182, v87
	v_max_f32_e32 v183, v183, v95
	v_max3_f32 v174, v96, v97, v98
	v_max3_f32 v175, v104, v105, v106
	v_max3_f32 v174, v174, v99, v100
	v_max3_f32 v175, v175, v107, v108
	v_max3_f32 v174, v174, v101, v102
	v_max3_f32 v175, v175, v109, v110
	v_max_f32_e32 v174, v174, v103
	v_max_f32_e32 v175, v175, v111
	v_max3_f32 v182, v182, v183, v174
	v_max_f32_e32 v182, v182, v175
	v_mov_b32_e32 v183, v182
	s_nop 1
	v_permlane32_swap_b32_e32 v182, v183
	v_max_f32_e32 v182, v182, v183
	v_cmp_lt_f32_e64 s[38:39], s23, v182
	v_cmp_lt_f32_e64 s[6:7], s75, v182
	s_andn2_b64 s[8:9], s[38:39], s[4:5]
	s_or_b64 s[4:5], s[4:5], s[38:39]
	s_or_b64 s[6:7], s[6:7], s[8:9]
	s_cbranch_scc1 .Lat_d1_rare
.Lat_d1_cont:
	v_exp_f32_e32 v80, v80
	v_exp_f32_e32 v81, v81
	v_exp_f32_e32 v82, v82
	v_exp_f32_e32 v83, v83
	v_exp_f32_e32 v84, v84
	v_exp_f32_e32 v85, v85
	v_exp_f32_e32 v86, v86
	v_exp_f32_e32 v87, v87
	v_cvt_pk_bf16_f32 v80, v80, v81
	v_cvt_pk_bf16_f32 v81, v82, v83
	v_cvt_pk_bf16_f32 v82, v84, v85
	v_cvt_pk_bf16_f32 v83, v86, v87
	ds_read_b64_tr_b16 v[84:85], v178 offset:28672
	ds_read_b64_tr_b16 v[86:87], v178 offset:29184
	s_waitcnt lgkmcnt(8)
	v_mfma_f32_32x32x16_bf16 v[16:31], v[64:67], v[80:83], v[16:31]
	v_exp_f32_e32 v88, v88
	v_exp_f32_e32 v89, v89
	v_exp_f32_e32 v90, v90
	s_waitcnt lgkmcnt(6)
	v_mfma_f32_32x32x16_bf16 v[0:15], v[68:71], v[80:83], v[0:15]
	v_exp_f32_e32 v91, v91
	v_exp_f32_e32 v92, v92
	v_exp_f32_e32 v93, v93
	v_mfma_f32_32x32x16_bf16 v[32:47], v[184:187], v[80:83], v[32:47]
	v_exp_f32_e32 v94, v94
	v_exp_f32_e32 v95, v95
	v_cvt_pk_bf16_f32 v88, v88, v89
	v_cvt_pk_bf16_f32 v89, v90, v91
	v_cvt_pk_bf16_f32 v90, v92, v93
	v_cvt_pk_bf16_f32 v91, v94, v95
	ds_read_b64_tr_b16 v[80:81], v178 offset:32768
	ds_read_b64_tr_b16 v[82:83], v178 offset:33280
	ds_read_b64_tr_b16 v[92:93], v178 offset:29696
	ds_read_b64_tr_b16 v[94:95], v178 offset:30208
	s_waitcnt lgkmcnt(8)
	v_mfma_f32_32x32x16_bf16 v[16:31], v[72:75], v[88:91], v[16:31]
	v_exp_f32_e32 v96, v96
	v_exp_f32_e32 v97, v97
	v_exp_f32_e32 v98, v98
	s_waitcnt lgkmcnt(6)
	v_mfma_f32_32x32x16_bf16 v[0:15], v[76:79], v[88:91], v[0:15]
	v_exp_f32_e32 v99, v99
	v_exp_f32_e32 v100, v100
	v_exp_f32_e32 v101, v101
	v_mfma_f32_32x32x16_bf16 v[32:47], v[184:187], v[88:91], v[32:47]
	v_exp_f32_e32 v102, v102
	v_exp_f32_e32 v103, v103
	v_cvt_pk_bf16_f32 v96, v96, v97
	v_cvt_pk_bf16_f32 v97, v98, v99
	v_cvt_pk_bf16_f32 v98, v100, v101
	v_cvt_pk_bf16_f32 v99, v102, v103
	ds_read_b64_tr_b16 v[88:89], v178 offset:33792
	ds_read_b64_tr_b16 v[90:91], v178 offset:34304
	s_waitcnt lgkmcnt(6)
	v_mfma_f32_32x32x16_bf16 v[16:31], v[84:87], v[96:99], v[16:31]
	v_exp_f32_e32 v104, v104
	v_exp_f32_e32 v105, v105
	v_exp_f32_e32 v106, v106
	s_waitcnt lgkmcnt(4)
	v_mfma_f32_32x32x16_bf16 v[0:15], v[80:83], v[96:99], v[0:15]
	v_exp_f32_e32 v107, v107
	v_exp_f32_e32 v108, v108
	v_exp_f32_e32 v109, v109
	v_mfma_f32_32x32x16_bf16 v[32:47], v[184:187], v[96:99], v[32:47]
	v_exp_f32_e32 v110, v110
	v_exp_f32_e32 v111, v111
	v_cvt_pk_bf16_f32 v104, v104, v105
	v_cvt_pk_bf16_f32 v105, v106, v107
	v_cvt_pk_bf16_f32 v106, v108, v109
	v_cvt_pk_bf16_f32 v107, v110, v111
	s_waitcnt lgkmcnt(2)
	s_nop 1
	v_mfma_f32_32x32x16_bf16 v[16:31], v[92:95], v[104:107], v[16:31]
	s_waitcnt lgkmcnt(0)
	v_mfma_f32_32x32x16_bf16 v[0:15], v[88:91], v[104:107], v[0:15]
	s_waitcnt vmcnt(4)
	s_cmp_lt_u32 s10, 62
	s_cbranch_scc1 .Lat_d_st1
	s_waitcnt vmcnt(0)
.Lat_d_st1:
	ds_write_b128 v172, v[144:147] offset:34816
	ds_write_b128 v173, v[148:151] offset:44032
	ds_write_b128 v172, v[152:155] offset:52224
	ds_write_b128 v173, v[156:159] offset:61440
	v_mfma_f32_32x32x16_bf16 v[32:47], v[184:187], v[104:107], v[32:47]
	s_waitcnt lgkmcnt(0)
	s_barrier
	ds_read_b128 v[64:67], v181 offset:34816
	ds_read_b128 v[68:71], v181 offset:34848
	ds_read_b128 v[72:75], v181 offset:34880
	ds_read_b128 v[76:79], v181 offset:34912
	s_cmp_gt_u32 s10, 60
	s_cbranch_scc1 .Lat_d_nold1
	v_lshl_add_u64 v[174:175], v[166:167], 0, v[176:177]
	v_add_co_u32_e32 v174, vcc, 0x18401000, v174
	s_nop 1
	v_addc_co_u32_e32 v175, vcc, 0, v175, vcc
	global_load_dwordx4 v[144:147], v[174:175], off offset:1024
	global_load_dwordx4 v[148:151], v[174:175], off offset:1280
	v_lshl_add_u64 v[174:175], v[164:165], 0, v[176:177]
	v_add_co_u32_e32 v174, vcc, 0x18401000, v174
	s_nop 1
	v_addc_co_u32_e32 v175, vcc, 0, v175, vcc
	global_load_dwordx4 v[152:155], v[174:175], off offset:1024
	global_load_dwordx4 v[156:159], v[174:175], off offset:1280
.Lat_d_nold1:
	s_waitcnt lgkmcnt(3)
	v_mfma_f32_32x32x16_bf16 v[80:95], v[64:67], v[120:123], v[48:63]
	ds_read_b128 v[64:67], v181 offset:39424
	s_waitcnt lgkmcnt(3)
	v_mfma_f32_32x32x16_bf16 v[80:95], v[68:71], v[112:115], v[80:95]
	ds_read_b128 v[68:71], v181 offset:39456
	s_waitcnt lgkmcnt(3)
	v_mfma_f32_32x32x16_bf16 v[80:95], v[72:75], v[116:119], v[80:95]
	ds_read_b128 v[72:75], v181 offset:39488
	s_waitcnt lgkmcnt(3)
	v_mfma_f32_32x32x16_bf16 v[80:95], v[76:79], v[124:127], v[80:95]
	ds_read_b128 v[76:79], v181 offset:39520
	s_waitcnt lgkmcnt(3)
	v_mfma_f32_32x32x16_bf16 v[96:111], v[64:67], v[120:123], v[48:63]
	s_waitcnt lgkmcnt(2)
	v_mfma_f32_32x32x16_bf16 v[96:111], v[68:71], v[112:115], v[96:111]
	s_waitcnt lgkmcnt(1)
	v_mfma_f32_32x32x16_bf16 v[96:111], v[72:75], v[116:119], v[96:111]
	s_waitcnt lgkmcnt(0)
	v_mfma_f32_32x32x16_bf16 v[96:111], v[76:79], v[124:127], v[96:111]
	ds_read_b64_tr_b16 v[64:65], v178 offset:44032
	ds_read_b64_tr_b16 v[66:67], v178 offset:44544
	ds_read_b64_tr_b16 v[68:69], v178 offset:48128
	ds_read_b64_tr_b16 v[70:71], v178 offset:48640
	ds_read_b64_tr_b16 v[72:73], v178 offset:45056
	ds_read_b64_tr_b16 v[74:75], v178 offset:45568
	ds_read_b64_tr_b16 v[76:77], v178 offset:49152
	ds_read_b64_tr_b16 v[78:79], v178 offset:49664
	v_max3_f32 v182, v80, v81, v82
	v_max3_f32 v183, v88, v89, v90
	v_max3_f32 v182, v182, v83, v84
	v_max3_f32 v183, v183, v91, v92
	v_max3_f32 v182, v182, v85, v86
	v_max3_f32 v183, v183, v93, v94
	v_max_f32_e32 v182, v182, v87
	v_max_f32_e32 v183, v183, v95
	v_max3_f32 v174, v96, v97, v98
	v_max3_f32 v175, v104, v105, v106
	v_max3_f32 v174, v174, v99, v100
	v_max3_f32 v175, v175, v107, v108
	v_max3_f32 v174, v174, v101, v102
	v_max3_f32 v175, v175, v109, v110
	v_max_f32_e32 v174, v174, v103
	v_max_f32_e32 v175, v175, v111
	v_max3_f32 v182, v182, v183, v174
	v_max_f32_e32 v182, v182, v175
	v_mov_b32_e32 v183, v182
	s_nop 1
	v_permlane32_swap_b32_e32 v182, v183
	v_max_f32_e32 v182, v182, v183
	v_cmp_lt_f32_e64 s[38:39], s23, v182
	v_cmp_lt_f32_e64 s[6:7], s75, v182
	s_andn2_b64 s[8:9], s[38:39], s[4:5]
	s_or_b64 s[4:5], s[4:5], s[38:39]
	s_or_b64 s[6:7], s[6:7], s[8:9]
	s_cbranch_scc1 .Lat_d2_rare
.Lat_d2_cont:
	v_exp_f32_e32 v80, v80
	v_exp_f32_e32 v81, v81
	v_exp_f32_e32 v82, v82
	v_exp_f32_e32 v83, v83
	v_exp_f32_e32 v84, v84
	v_exp_f32_e32 v85, v85
	v_exp_f32_e32 v86, v86
	v_exp_f32_e32 v87, v87
	v_cvt_pk_bf16_f32 v80, v80, v81
	v_cvt_pk_bf16_f32 v81, v82, v83
	v_cvt_pk_bf16_f32 v82, v84, v85
	v_cvt_pk_bf16_f32 v83, v86, v87
	ds_read_b64_tr_b16 v[84:85], v178 offset:46080
	ds_read_b64_tr_b16 v[86:87], v178 offset:46592
	s_waitcnt lgkmcnt(8)
	v_mfma_f32_32x32x16_bf16 v[16:31], v[64:67], v[80:83], v[16:31]
	v_exp_f32_e32 v88, v88
	v_exp_f32_e32 v89, v89
	v_exp_f32_e32 v90, v90
	s_waitcnt lgkmcnt(6)
	v_mfma_f32_32x32x16_bf16 v[0:15], v[68:71], v[80:83], v[0:15]
	v_exp_f32_e32 v91, v91
	v_exp_f32_e32 v92, v92
	v_exp_f32_e32 v93, v93
	v_mfma_f32_32x32x16_bf16 v[32:47], v[184:187], v[80:83], v[32:47]
	v_exp_f32_e32 v94, v94
	v_exp_f32_e32 v95, v95
	v_cvt_pk_bf16_f32 v88, v88, v89
	v_cvt_pk_bf16_f32 v89, v90, v91
	v_cvt_pk_bf16_f32 v90, v92, v93
	v_cvt_pk_bf16_f32 v91, v94, v95
	ds_read_b64_tr_b16 v[80:81], v178 offset:50176
	ds_read_b64_tr_b16 v[82:83], v178 offset:50688
	ds_read_b64_tr_b16 v[92:93], v178 offset:47104
	ds_read_b64_tr_b16 v[94:95], v178 offset:47616
	s_waitcnt lgkmcnt(8)
	v_mfma_f32_32x32x16_bf16 v[16:31], v[72:75], v[88:91], v[16:31]
	v_exp_f32_e32 v96, v96
	v_exp_f32_e32 v97, v97
	v_exp_f32_e32 v98, v98
	s_waitcnt lgkmcnt(6)
	v_mfma_f32_32x32x16_bf16 v[0:15], v[76:79], v[88:91], v[0:15]
	v_exp_f32_e32 v99, v99
	v_exp_f32_e32 v100, v100
	v_exp_f32_e32 v101, v101
	v_mfma_f32_32x32x16_bf16 v[32:47], v[184:187], v[88:91], v[32:47]
	v_exp_f32_e32 v102, v102
	v_exp_f32_e32 v103, v103
	v_cvt_pk_bf16_f32 v96, v96, v97
	v_cvt_pk_bf16_f32 v97, v98, v99
	v_cvt_pk_bf16_f32 v98, v100, v101
	v_cvt_pk_bf16_f32 v99, v102, v103
	ds_read_b64_tr_b16 v[88:89], v178 offset:51200
	ds_read_b64_tr_b16 v[90:91], v178 offset:51712
	ds_read_b128 v[64:67], v181 offset:52224
	ds_read_b128 v[68:71], v181 offset:52256
	ds_read_b128 v[72:75], v181 offset:52288
	ds_read_b128 v[76:79], v181 offset:52320
	s_waitcnt lgkmcnt(10)
	v_mfma_f32_32x32x16_bf16 v[16:31], v[84:87], v[96:99], v[16:31]
	v_exp_f32_e32 v104, v104
	v_exp_f32_e32 v105, v105
	v_exp_f32_e32 v106, v106
	s_waitcnt lgkmcnt(8)
	v_mfma_f32_32x32x16_bf16 v[0:15], v[80:83], v[96:99], v[0:15]
	v_exp_f32_e32 v107, v107
	v_exp_f32_e32 v108, v108
	v_exp_f32_e32 v109, v109
	v_mfma_f32_32x32x16_bf16 v[32:47], v[184:187], v[96:99], v[32:47]
	v_exp_f32_e32 v110, v110
	v_exp_f32_e32 v111, v111
	v_cvt_pk_bf16_f32 v104, v104, v105
	v_cvt_pk_bf16_f32 v105, v106, v107
	v_cvt_pk_bf16_f32 v106, v108, v109
	v_cvt_pk_bf16_f32 v107, v110, v111
	s_waitcnt lgkmcnt(6)
	s_nop 1
	v_mfma_f32_32x32x16_bf16 v[16:31], v[92:95], v[104:107], v[16:31]
	s_waitcnt lgkmcnt(4)
	v_mfma_f32_32x32x16_bf16 v[0:15], v[88:91], v[104:107], v[0:15]
	v_mfma_f32_32x32x16_bf16 v[32:47], v[184:187], v[104:107], v[32:47]
	s_waitcnt lgkmcnt(3)
	v_mfma_f32_32x32x16_bf16 v[80:95], v[64:67], v[120:123], v[48:63]
	ds_read_b128 v[64:67], v181 offset:56832
	s_waitcnt lgkmcnt(3)
	v_mfma_f32_32x32x16_bf16 v[80:95], v[68:71], v[112:115], v[80:95]
	ds_read_b128 v[68:71], v181 offset:56864
	s_waitcnt lgkmcnt(3)
	v_mfma_f32_32x32x16_bf16 v[80:95], v[72:75], v[116:119], v[80:95]
	ds_read_b128 v[72:75], v181 offset:56896
	s_waitcnt lgkmcnt(3)
	v_mfma_f32_32x32x16_bf16 v[80:95], v[76:79], v[124:127], v[80:95]
	ds_read_b128 v[76:79], v181 offset:56928
	s_waitcnt lgkmcnt(3)
	v_mfma_f32_32x32x16_bf16 v[96:111], v[64:67], v[120:123], v[48:63]
	s_waitcnt lgkmcnt(2)
	v_mfma_f32_32x32x16_bf16 v[96:111], v[68:71], v[112:115], v[96:111]
	s_waitcnt lgkmcnt(1)
	v_mfma_f32_32x32x16_bf16 v[96:111], v[72:75], v[116:119], v[96:111]
	s_waitcnt lgkmcnt(0)
	v_mfma_f32_32x32x16_bf16 v[96:111], v[76:79], v[124:127], v[96:111]
	ds_read_b64_tr_b16 v[64:65], v179 offset:0
	ds_read_b64_tr_b16 v[66:67], v179 offset:512
	ds_read_b64_tr_b16 v[68:69], v179 offset:4096
	ds_read_b64_tr_b16 v[70:71], v179 offset:4608
	ds_read_b64_tr_b16 v[72:73], v179 offset:1024
	ds_read_b64_tr_b16 v[74:75], v179 offset:1536
	ds_read_b64_tr_b16 v[76:77], v179 offset:5120
	ds_read_b64_tr_b16 v[78:79], v179 offset:5632
	v_max3_f32 v182, v80, v81, v82
	v_max3_f32 v183, v88, v89, v90
	v_max3_f32 v182, v182, v83, v84
	v_max3_f32 v183, v183, v91, v92
	v_max3_f32 v182, v182, v85, v86
	v_max3_f32 v183, v183, v93, v94
	v_max_f32_e32 v182, v182, v87
	v_max_f32_e32 v183, v183, v95
	v_max3_f32 v174, v96, v97, v98
	v_max3_f32 v175, v104, v105, v106
	v_max3_f32 v174, v174, v99, v100
	v_max3_f32 v175, v175, v107, v108
	v_max3_f32 v174, v174, v101, v102
	v_max3_f32 v175, v175, v109, v110
	v_max_f32_e32 v174, v174, v103
	v_max_f32_e32 v175, v175, v111
	v_max3_f32 v182, v182, v183, v174
	v_max_f32_e32 v182, v182, v175
	v_mov_b32_e32 v183, v182
	s_nop 1
	v_permlane32_swap_b32_e32 v182, v183
	v_max_f32_e32 v182, v182, v183
	v_cmp_lt_f32_e64 s[38:39], s23, v182
	v_cmp_lt_f32_e64 s[6:7], s75, v182
	s_andn2_b64 s[8:9], s[38:39], s[4:5]
	s_or_b64 s[4:5], s[4:5], s[38:39]
	s_or_b64 s[6:7], s[6:7], s[8:9]
	s_cbranch_scc1 .Lat_d3_rare
.Lat_d3_cont:
	v_exp_f32_e32 v80, v80
	v_exp_f32_e32 v81, v81
	v_exp_f32_e32 v82, v82
	v_exp_f32_e32 v83, v83
	v_exp_f32_e32 v84, v84
	v_exp_f32_e32 v85, v85
	v_exp_f32_e32 v86, v86
	v_exp_f32_e32 v87, v87
	v_cvt_pk_bf16_f32 v80, v80, v81
	v_cvt_pk_bf16_f32 v81, v82, v83
	v_cvt_pk_bf16_f32 v82, v84, v85
	v_cvt_pk_bf16_f32 v83, v86, v87
	ds_read_b64_tr_b16 v[84:85], v179 offset:2048
	ds_read_b64_tr_b16 v[86:87], v179 offset:2560
	s_waitcnt lgkmcnt(8)
	v_mfma_f32_32x32x16_bf16 v[16:31], v[64:67], v[80:83], v[16:31]
	v_exp_f32_e32 v88, v88
	v_exp_f32_e32 v89, v89
	v_exp_f32_e32 v90, v90
	s_waitcnt lgkmcnt(6)
	v_mfma_f32_32x32x16_bf16 v[0:15], v[68:71], v[80:83], v[0:15]
	v_exp_f32_e32 v91, v91
	v_exp_f32_e32 v92, v92
	v_exp_f32_e32 v93, v93
	v_mfma_f32_32x32x16_bf16 v[32:47], v[184:187], v[80:83], v[32:47]
	v_exp_f32_e32 v94, v94
	v_exp_f32_e32 v95, v95
	v_cvt_pk_bf16_f32 v88, v88, v89
	v_cvt_pk_bf16_f32 v89, v90, v91
	v_cvt_pk_bf16_f32 v90, v92, v93
	v_cvt_pk_bf16_f32 v91, v94, v95
	ds_read_b64_tr_b16 v[80:81], v179 offset:6144
	ds_read_b64_tr_b16 v[82:83], v179 offset:6656
	ds_read_b64_tr_b16 v[92:93], v179 offset:3072
	ds_read_b64_tr_b16 v[94:95], v179 offset:3584
	s_waitcnt lgkmcnt(8)
	v_mfma_f32_32x32x16_bf16 v[16:31], v[72:75], v[88:91], v[16:31]
	v_exp_f32_e32 v96, v96
	v_exp_f32_e32 v97, v97
	v_exp_f32_e32 v98, v98
	s_waitcnt lgkmcnt(6)
	v_mfma_f32_32x32x16_bf16 v[0:15], v[76:79], v[88:91], v[0:15]
	v_exp_f32_e32 v99, v99
	v_exp_f32_e32 v100, v100
	v_exp_f32_e32 v101, v101
	v_mfma_f32_32x32x16_bf16 v[32:47], v[184:187], v[88:91], v[32:47]
	v_exp_f32_e32 v102, v102
	v_exp_f32_e32 v103, v103
	v_cvt_pk_bf16_f32 v96, v96, v97
	v_cvt_pk_bf16_f32 v97, v98, v99
	v_cvt_pk_bf16_f32 v98, v100, v101
	v_cvt_pk_bf16_f32 v99, v102, v103
	ds_read_b64_tr_b16 v[88:89], v179 offset:7168
	ds_read_b64_tr_b16 v[90:91], v179 offset:7680
	s_waitcnt lgkmcnt(6)
	v_mfma_f32_32x32x16_bf16 v[16:31], v[84:87], v[96:99], v[16:31]
	v_exp_f32_e32 v104, v104
	v_exp_f32_e32 v105, v105
	v_exp_f32_e32 v106, v106
	s_waitcnt lgkmcnt(4)
	v_mfma_f32_32x32x16_bf16 v[0:15], v[80:83], v[96:99], v[0:15]
	v_exp_f32_e32 v107, v107
	v_exp_f32_e32 v108, v108
	v_exp_f32_e32 v109, v109
	v_mfma_f32_32x32x16_bf16 v[32:47], v[184:187], v[96:99], v[32:47]
	v_exp_f32_e32 v110, v110
	v_exp_f32_e32 v111, v111
	v_cvt_pk_bf16_f32 v104, v104, v105
	v_cvt_pk_bf16_f32 v105, v106, v107
	v_cvt_pk_bf16_f32 v106, v108, v109
	v_cvt_pk_bf16_f32 v107, v110, v111
	s_waitcnt lgkmcnt(2)
	s_nop 1
	v_mfma_f32_32x32x16_bf16 v[16:31], v[92:95], v[104:107], v[16:31]
	s_waitcnt lgkmcnt(0)
	v_mfma_f32_32x32x16_bf16 v[0:15], v[88:91], v[104:107], v[0:15]
	s_cmp_gt_u32 s10, 61
	s_cbranch_scc1 .Lat_d_st0
	s_waitcnt vmcnt(4)
	ds_write_b128 v172, v[128:131]
	ds_write_b128 v173, v[132:135] offset:9216
	ds_write_b128 v172, v[136:139] offset:17408
	ds_write_b128 v173, v[140:143] offset:26624
.Lat_d_st0:
	v_mfma_f32_32x32x16_bf16 v[32:47], v[184:187], v[104:107], v[32:47]
	s_mov_b64 s[2:3], 0x160000
	v_readlane_b32 s20, v255, 38
	v_lshl_add_u64 v[164:165], v[164:165], 0, s[2:3]
	v_lshl_add_u64 v[166:167], v[166:167], 0, s[2:3]
	v_lshl_add_u64 v[168:169], v[168:169], 0, s[2:3]
	v_lshl_add_u64 v[170:171], v[170:171], 0, s[2:3]
	v_readlane_b32 s21, v255, 39
	s_add_i32 s10, s10, 2
	s_waitcnt lgkmcnt(0)
	s_barrier
	s_cmp_lt_u32 s10, 64
	s_cbranch_scc1 .Lat_d_top
	s_branch .LBB0_464
.Lat_d0_rare:
	s_nop 7
	v_cndmask_b32_e64 v174, 0, v182, s[6:7]
	s_nop 0
	v_exp_f32_e64 v175, -v174
	v_add_f32_e32 v180, v180, v174
	v_sub_f32_e32 v80, v80, v174
	v_sub_f32_e32 v81, v81, v174
	v_sub_f32_e32 v82, v82, v174
	v_sub_f32_e32 v83, v83, v174
	v_sub_f32_e32 v84, v84, v174
	v_sub_f32_e32 v85, v85, v174
	v_sub_f32_e32 v86, v86, v174
	v_sub_f32_e32 v87, v87, v174
	v_sub_f32_e32 v88, v88, v174
	v_sub_f32_e32 v89, v89, v174
	v_sub_f32_e32 v90, v90, v174
	v_sub_f32_e32 v91, v91, v174
	v_sub_f32_e32 v92, v92, v174
	v_sub_f32_e32 v93, v93, v174
	v_sub_f32_e32 v94, v94, v174
	v_sub_f32_e32 v95, v95, v174
	v_sub_f32_e32 v96, v96, v174
	v_sub_f32_e32 v97, v97, v174
	v_sub_f32_e32 v98, v98, v174
	v_sub_f32_e32 v99, v99, v174
	v_sub_f32_e32 v100, v100, v174
	v_sub_f32_e32 v101, v101, v174
	v_sub_f32_e32 v102, v102, v174
	v_sub_f32_e32 v103, v103, v174
	v_sub_f32_e32 v104, v104, v174
	v_sub_f32_e32 v105, v105, v174
	v_sub_f32_e32 v106, v106, v174
	v_sub_f32_e32 v107, v107, v174
	v_sub_f32_e32 v108, v108, v174
	v_sub_f32_e32 v109, v109, v174
	v_sub_f32_e32 v110, v110, v174
	v_sub_f32_e32 v111, v111, v174
	v_mul_f32_e32 v16, v16, v175
	v_mul_f32_e32 v17, v17, v175
	v_mul_f32_e32 v18, v18, v175
	v_mul_f32_e32 v19, v19, v175
	v_mul_f32_e32 v20, v20, v175
	v_mul_f32_e32 v21, v21, v175
	v_mul_f32_e32 v22, v22, v175
	v_mul_f32_e32 v23, v23, v175
	v_mul_f32_e32 v24, v24, v175
	v_mul_f32_e32 v25, v25, v175
	v_mul_f32_e32 v26, v26, v175
	v_mul_f32_e32 v27, v27, v175
	v_mul_f32_e32 v28, v28, v175
	v_mul_f32_e32 v29, v29, v175
	v_mul_f32_e32 v30, v30, v175
	v_mul_f32_e32 v31, v31, v175
	v_mul_f32_e32 v0, v0, v175
	v_mul_f32_e32 v1, v1, v175
	v_mul_f32_e32 v2, v2, v175
	v_mul_f32_e32 v3, v3, v175
	v_mul_f32_e32 v4, v4, v175
	v_mul_f32_e32 v5, v5, v175
	v_mul_f32_e32 v6, v6, v175
	v_mul_f32_e32 v7, v7, v175
	v_mul_f32_e32 v8, v8, v175
	v_mul_f32_e32 v9, v9, v175
	v_mul_f32_e32 v10, v10, v175
	v_mul_f32_e32 v11, v11, v175
	v_mul_f32_e32 v12, v12, v175
	v_mul_f32_e32 v13, v13, v175
	v_mul_f32_e32 v14, v14, v175
	v_mul_f32_e32 v15, v15, v175
	v_mul_f32_e32 v32, v32, v175
	v_mul_f32_e32 v33, v33, v175
	v_mul_f32_e32 v34, v34, v175
	v_mul_f32_e32 v35, v35, v175
	v_mul_f32_e32 v36, v36, v175
	v_mul_f32_e32 v37, v37, v175
	v_mul_f32_e32 v38, v38, v175
	v_mul_f32_e32 v39, v39, v175
	v_mul_f32_e32 v40, v40, v175
	v_mul_f32_e32 v41, v41, v175
	v_mul_f32_e32 v42, v42, v175
	v_mul_f32_e32 v43, v43, v175
	v_mul_f32_e32 v44, v44, v175
	v_mul_f32_e32 v45, v45, v175
	v_mul_f32_e32 v46, v46, v175
	v_mul_f32_e32 v47, v47, v175
	v_xor_b32_e32 v48, 0x80000000, v180
	s_nop 0
	v_mov_b32_e32 v49, v48
	v_mov_b32_e32 v50, v48
	v_mov_b32_e32 v51, v48
	v_mov_b32_e32 v52, v48
	v_mov_b32_e32 v53, v48
	v_mov_b32_e32 v54, v48
	v_mov_b32_e32 v55, v48
	v_mov_b32_e32 v56, v48
	v_mov_b32_e32 v57, v48
	v_mov_b32_e32 v58, v48
	v_mov_b32_e32 v59, v48
	v_mov_b32_e32 v60, v48
	v_mov_b32_e32 v61, v48
	v_mov_b32_e32 v62, v48
	v_mov_b32_e32 v63, v48
	s_branch .Lat_d0_cont
